# gate/up epilogue prologue: workspace pointer taken from the per-phase spill lanes instead of a kernarg s_load round trip
# baseline (speedup 1.0000x reference)
.LBB0_515:
	v_readlane_b32 s88, v254, 53
	s_andn2_b64 vcc, exec, s[92:93]
	v_readlane_b32 s89, v254, 54
	v_readlane_b32 s92, v254, 55
	v_readlane_b32 s64, v254, 56
	v_readlane_b32 s65, v254, 57
	s_cbranch_vccnz .LBB0_519
	v_readlane_b32 s12, v253, 41
	v_readlane_b32 s13, v253, 42
	s_cmp_lt_u32 s34, 32
	s_mov_b64 s[14:15], 0
	s_cbranch_scc1 .LBB0_518
	s_sub_i32 s10, s34, 32
	s_lshr_b32 s10, s10, 2
	s_add_i32 s10, s10, 1
	s_mul_hi_u32 s15, s10, 0x3500
	s_mul_i32 s14, s10, 0x3500
